# in-projection GEMM transposed-store epilogue: wave-private LDS image, 16-byte stores along token rows (16 store instructions per wave instead of 128 two-byte ones)
# baseline (speedup 1.0000x reference)
; template <bool AT>
; DI void gemm_main(f32x16 (&acc)[2][4], const u16* __restrict__ R, int ldr, const u16* __restrict__ Cm, int ldc,
;                   const u16* __restrict__ RT, int ldrt, int K, char* smem, int tid) {
;     ...
;   for (int kt = -1; kt < nk; ++kt) {
;     if (kt + 1 < nk) {
;       const int ks1 = kt + 1;
;       u16* Rs = S0 + (ks1 & 1) * STG;
;       u16* Cs = Rs + 256 * 72;
; #pragma unroll
;       for (int i = 0; i < 4; ++i) {
;         const int cid = tid + NT * i;
;         const int row = cid >> 3, kc = cid & 7;
;         if (AT && ks1 < 8) {
;           const int kr = cid >> 5, tc = cid & 31;
;           *(u32x4*)(Rs + kr * 264 + tc * 8) = rr[i];
;         } else {
;           *(u32x4*)(Rs + row * 72 + kc * 8) = rr[i];
;         }
;         *(u32x4*)(Cs + row * 72 + kc * 8) = cr[i];
;       }
;     }
;     if (kt + 2 < nk) {
;       const int kn = kt + 2;
; #pragma unroll
;       for (int i = 0; i < 4; ++i) {
;         const int cid = tid + NT * i;
;         const int row = cid >> 3, kc = cid & 7;
;         if (AT && kn < 8) {
;           const int kr = cid >> 5, tc = cid & 31;
;           rr[i] = *(const u32x4*)(RT + (size_t)(kn * 64 + kr) * ldrt + tc * 8);
;         } else {
;           rr[i] = *(const u32x4*)(R + (size_t)row * ldr + kn * 64 + kc * 8);
;         }
;         cr[i] = *(const u32x4*)(Cm + (size_t)row * ldc + kn * 64 + kc * 8);
;       }
;     }
;     __builtin_amdgcn_sched_barrier(0x38F);
;     if (kt >= 0) {
;       const u16* Rs = S0 + (kt & 1) * STG;
;       const u16* Cs = Rs + 256 * 72;
;       const u16* RTs = Rs;
; #pragma unroll
;       for (int ks = 0; ks < 4; ++ks) {
;         bf16x8 rf[2];
; #pragma unroll
;         for (int rb = 0; rb < 2; ++rb) {
;           if (AT && kt < 8) {
;             const u16* src = RTs + (16 * ks + 8 * g) * 264 + 64 * wr + 32 * rb + li;
;             bf16x8 t;
; #pragma unroll
;             for (int j = 0; j < 8; ++j) t[j] = (short)src[j * 264];
;             rf[rb] = t;
;           } else {
;             rf[rb] = *(const bf16x8*)(Rs + (64 * wr + 32 * rb + li) * 72 + 16 * ks + 8 * g);
;           }
;         }
; #pragma unroll
;         for (int cb = 0; cb < 4; ++cb) {
;           const bf16x8 cfv = *(const bf16x8*)(Cs + (128 * wc + 32 * cb + li) * 72 + 16 * ks + 8 * g);
; #pragma unroll
;           for (int rb = 0; rb < 2; ++rb) acc[rb][cb] = MFMA(rf[rb], cfv, acc[rb][cb]);
.Lgn_loop:
	ds_read_b128 v[192:195], v190 offset:0
	ds_read_b128 v[220:223], v190 offset:4608
	ds_read_b128 v[232:235], v191 offset:36864
	ds_read_b128 v[236:239], v191 offset:41472
	ds_read_b128 v[240:243], v191 offset:46080
	ds_read_b128 v[244:247], v191 offset:50688
	ds_read_b128 v[224:227], v190 offset:32
	ds_read_b128 v[228:231], v190 offset:4640
	s_waitcnt lgkmcnt(5)
	v_mfma_f32_32x32x16_bf16 v[112:127], v[192:195], v[232:235], v[112:127]
	v_mfma_f32_32x32x16_bf16 v[96:111], v[220:223], v[232:235], v[96:111]
	ds_read_b128 v[232:235], v191 offset:36896
	s_waitcnt vmcnt(0)
	ds_write_b128 v196, v[152:155]
	s_waitcnt lgkmcnt(6)
	v_mfma_f32_32x32x16_bf16 v[80:95], v[192:195], v[236:239], v[80:95]
	v_mfma_f32_32x32x16_bf16 v[64:79], v[220:223], v[236:239], v[64:79]
	ds_read_b128 v[236:239], v191 offset:41504
	ds_write_b128 v196, v[136:139] offset:36864
	s_waitcnt lgkmcnt(7)
	v_mfma_f32_32x32x16_bf16 v[48:63], v[192:195], v[240:243], v[48:63]
	v_mfma_f32_32x32x16_bf16 v[32:47], v[220:223], v[240:243], v[32:47]
	ds_read_b128 v[240:243], v191 offset:46112
	ds_write_b128 v197, v[148:151]
	s_waitcnt lgkmcnt(8)
	v_mfma_f32_32x32x16_bf16 v[16:31], v[192:195], v[244:247], v[16:31]
	v_mfma_f32_32x32x16_bf16 v[0:15], v[220:223], v[244:247], v[0:15]
	ds_read_b128 v[244:247], v191 offset:50720
	ds_write_b128 v197, v[132:135] offset:36864
	ds_read_b128 v[192:195], v190 offset:64
	ds_read_b128 v[220:223], v190 offset:4672
	s_waitcnt lgkmcnt(9)
	v_mfma_f32_32x32x16_bf16 v[112:127], v[224:227], v[232:235], v[112:127]
	v_mfma_f32_32x32x16_bf16 v[96:111], v[228:231], v[232:235], v[96:111]
	ds_read_b128 v[232:235], v191 offset:36928
	ds_write_b128 v249, v[144:147]
	s_waitcnt lgkmcnt(9)
	v_mfma_f32_32x32x16_bf16 v[80:95], v[224:227], v[236:239], v[80:95]
	v_mfma_f32_32x32x16_bf16 v[64:79], v[228:231], v[236:239], v[64:79]
	ds_read_b128 v[236:239], v191 offset:41536
	ds_write_b128 v249, v[128:131] offset:36864
	s_waitcnt lgkmcnt(9)
	v_mfma_f32_32x32x16_bf16 v[48:63], v[224:227], v[240:243], v[48:63]
	v_mfma_f32_32x32x16_bf16 v[32:47], v[228:231], v[240:243], v[32:47]
	ds_read_b128 v[240:243], v191 offset:46144
	ds_write_b128 v250, v[140:143]
	s_waitcnt lgkmcnt(9)
	v_mfma_f32_32x32x16_bf16 v[16:31], v[224:227], v[244:247], v[16:31]
	v_mfma_f32_32x32x16_bf16 v[0:15], v[228:231], v[244:247], v[0:15]
	ds_read_b128 v[244:247], v191 offset:50752
	ds_write_b128 v250, v[156:159] offset:36864
	ds_read_b128 v[224:227], v190 offset:96
	ds_read_b128 v[228:231], v190 offset:4704
	s_waitcnt lgkmcnt(9)
	v_mfma_f32_32x32x16_bf16 v[112:127], v[192:195], v[232:235], v[112:127]
	v_mfma_f32_32x32x16_bf16 v[96:111], v[220:223], v[232:235], v[96:111]
	ds_read_b128 v[232:235], v191 offset:36960
	v_subrev_u32_e32 v196, 0x12000, v196
	global_load_dwordx4 v[152:155], v[174:175], off
	v_lshl_add_u64 v[174:175], v[174:175], 0, s[58:59]
	s_waitcnt lgkmcnt(8)
	v_mfma_f32_32x32x16_bf16 v[80:95], v[192:195], v[236:239], v[80:95]
	v_mfma_f32_32x32x16_bf16 v[64:79], v[220:223], v[236:239], v[64:79]
	ds_read_b128 v[236:239], v191 offset:41568
	v_subrev_u32_e32 v197, 0x12000, v197
	global_load_dwordx4 v[136:139], v[166:167], off
	v_lshl_add_u64 v[166:167], v[166:167], 0, s[58:59]
	s_waitcnt lgkmcnt(7)
	v_mfma_f32_32x32x16_bf16 v[48:63], v[192:195], v[240:243], v[48:63]
	v_mfma_f32_32x32x16_bf16 v[32:47], v[220:223], v[240:243], v[32:47]
	ds_read_b128 v[240:243], v191 offset:46176
	v_subrev_u32_e32 v249, 0x12000, v249
	global_load_dwordx4 v[148:151], v[172:173], off
	v_lshl_add_u64 v[172:173], v[172:173], 0, s[58:59]
	s_waitcnt lgkmcnt(6)
	v_mfma_f32_32x32x16_bf16 v[16:31], v[192:195], v[244:247], v[16:31]
	v_mfma_f32_32x32x16_bf16 v[0:15], v[220:223], v[244:247], v[0:15]
	ds_read_b128 v[244:247], v191 offset:50784
	v_subrev_u32_e32 v250, 0x12000, v250
	global_load_dwordx4 v[132:135], v[164:165], off
	v_lshl_add_u64 v[164:165], v[164:165], 0, s[58:59]
	v_add_u32_e32 v190, 0x12000, v190
	v_add_u32_e32 v191, 0x12000, v191
	s_waitcnt lgkmcnt(3)
	v_mfma_f32_32x32x16_bf16 v[112:127], v[224:227], v[232:235], v[112:127]
	v_mfma_f32_32x32x16_bf16 v[96:111], v[228:231], v[232:235], v[96:111]
	global_load_dwordx4 v[144:147], v[170:171], off
	v_lshl_add_u64 v[170:171], v[170:171], 0, s[58:59]
	s_waitcnt lgkmcnt(2)
	v_mfma_f32_32x32x16_bf16 v[80:95], v[224:227], v[236:239], v[80:95]
	v_mfma_f32_32x32x16_bf16 v[64:79], v[228:231], v[236:239], v[64:79]
	global_load_dwordx4 v[128:131], v[162:163], off
	v_lshl_add_u64 v[162:163], v[162:163], 0, s[58:59]
	s_waitcnt lgkmcnt(1)
	v_mfma_f32_32x32x16_bf16 v[48:63], v[224:227], v[240:243], v[48:63]
	v_mfma_f32_32x32x16_bf16 v[32:47], v[228:231], v[240:243], v[32:47]
	global_load_dwordx4 v[140:143], v[168:169], off
	v_lshl_add_u64 v[168:169], v[168:169], 0, s[58:59]
	s_waitcnt lgkmcnt(0)
	v_mfma_f32_32x32x16_bf16 v[16:31], v[224:227], v[244:247], v[16:31]
	v_mfma_f32_32x32x16_bf16 v[0:15], v[228:231], v[244:247], v[0:15]
	global_load_dwordx4 v[156:159], v[160:161], off
	v_lshl_add_u64 v[160:161], v[160:161], 0, s[58:59]
	s_waitcnt lgkmcnt(0)
	s_barrier
; template <bool AT>
; DI void gemm_main(f32x16 (&acc)[2][4], const u16* __restrict__ R, int ldr, const u16* __restrict__ Cm, int ldc,
;                   const u16* __restrict__ RT, int ldrt, int K, char* smem, int tid) {
;     ...
;   for (int kt = -1; kt < nk; ++kt) {
;     if (kt + 1 < nk) {
;       const int ks1 = kt + 1;
;       u16* Rs = S0 + (ks1 & 1) * STG;
;       u16* Cs = Rs + 256 * 72;
; #pragma unroll
;       for (int i = 0; i < 4; ++i) {
;         const int cid = tid + NT * i;
;         const int row = cid >> 3, kc = cid & 7;
;         if (AT && ks1 < 8) {
;           const int kr = cid >> 5, tc = cid & 31;
;           *(u32x4*)(Rs + kr * 264 + tc * 8) = rr[i];
;         } else {
;           *(u32x4*)(Rs + row * 72 + kc * 8) = rr[i];
;         }
;         *(u32x4*)(Cs + row * 72 + kc * 8) = cr[i];
;       }
;     }
;     if (kt + 2 < nk) {
;       const int kn = kt + 2;
; #pragma unroll
;       for (int i = 0; i < 4; ++i) {
;         const int cid = tid + NT * i;
;         const int row = cid >> 3, kc = cid & 7;
;         if (AT && kn < 8) {
;           const int kr = cid >> 5, tc = cid & 31;
;           rr[i] = *(const u32x4*)(RT + (size_t)(kn * 64 + kr) * ldrt + tc * 8);
;         } else {
;           rr[i] = *(const u32x4*)(R + (size_t)row * ldr + kn * 64 + kc * 8);
;         }
;         cr[i] = *(const u32x4*)(Cm + (size_t)row * ldc + kn * 64 + kc * 8);
;       }
;     }
;     __builtin_amdgcn_sched_barrier(0x38F);
;     if (kt >= 0) {
;       const u16* Rs = S0 + (kt & 1) * STG;
;       const u16* Cs = Rs + 256 * 72;
;       const u16* RTs = Rs;
; #pragma unroll
;       for (int ks = 0; ks < 4; ++ks) {
;         bf16x8 rf[2];
; #pragma unroll
;         for (int rb = 0; rb < 2; ++rb) {
;           if (AT && kt < 8) {
;             const u16* src = RTs + (16 * ks + 8 * g) * 264 + 64 * wr + 32 * rb + li;
;             bf16x8 t;
; #pragma unroll
;             for (int j = 0; j < 8; ++j) t[j] = (short)src[j * 264];
;             rf[rb] = t;
;           } else {
;             rf[rb] = *(const bf16x8*)(Rs + (64 * wr + 32 * rb + li) * 72 + 16 * ks + 8 * g);
;           }
;         }
; #pragma unroll
;         for (int cb = 0; cb < 4; ++cb) {
;           const bf16x8 cfv = *(const bf16x8*)(Cs + (128 * wc + 32 * cb + li) * 72 + 16 * ks + 8 * g);
; #pragma unroll
;           for (int rb = 0; rb < 2; ++rb) acc[rb][cb] = MFMA(rf[rb], cfv, acc[rb][cb]);
	ds_read_b128 v[192:195], v190 offset:0
	ds_read_b128 v[220:223], v190 offset:4608
	ds_read_b128 v[232:235], v191 offset:36864
	ds_read_b128 v[236:239], v191 offset:41472
	ds_read_b128 v[240:243], v191 offset:46080
	ds_read_b128 v[244:247], v191 offset:50688
	ds_read_b128 v[224:227], v190 offset:32
	ds_read_b128 v[228:231], v190 offset:4640
	s_waitcnt lgkmcnt(5)
	v_mfma_f32_32x32x16_bf16 v[112:127], v[192:195], v[232:235], v[112:127]
	v_mfma_f32_32x32x16_bf16 v[96:111], v[220:223], v[232:235], v[96:111]
	ds_read_b128 v[232:235], v191 offset:36896
	s_waitcnt vmcnt(0)
	ds_write_b128 v196, v[152:155]
	s_waitcnt lgkmcnt(6)
	v_mfma_f32_32x32x16_bf16 v[80:95], v[192:195], v[236:239], v[80:95]
	v_mfma_f32_32x32x16_bf16 v[64:79], v[220:223], v[236:239], v[64:79]
	ds_read_b128 v[236:239], v191 offset:41504
	ds_write_b128 v196, v[136:139] offset:36864
	s_waitcnt lgkmcnt(7)
	v_mfma_f32_32x32x16_bf16 v[48:63], v[192:195], v[240:243], v[48:63]
	v_mfma_f32_32x32x16_bf16 v[32:47], v[220:223], v[240:243], v[32:47]
	ds_read_b128 v[240:243], v191 offset:46112
	ds_write_b128 v197, v[148:151]
	s_waitcnt lgkmcnt(8)
	v_mfma_f32_32x32x16_bf16 v[16:31], v[192:195], v[244:247], v[16:31]
	v_mfma_f32_32x32x16_bf16 v[0:15], v[220:223], v[244:247], v[0:15]
	ds_read_b128 v[244:247], v191 offset:50720
	ds_write_b128 v197, v[132:135] offset:36864
	ds_read_b128 v[192:195], v190 offset:64
	ds_read_b128 v[220:223], v190 offset:4672
	s_waitcnt lgkmcnt(9)
	v_mfma_f32_32x32x16_bf16 v[112:127], v[224:227], v[232:235], v[112:127]
	v_mfma_f32_32x32x16_bf16 v[96:111], v[228:231], v[232:235], v[96:111]
	ds_read_b128 v[232:235], v191 offset:36928
	ds_write_b128 v249, v[144:147]
	s_waitcnt lgkmcnt(9)
	v_mfma_f32_32x32x16_bf16 v[80:95], v[224:227], v[236:239], v[80:95]
	v_mfma_f32_32x32x16_bf16 v[64:79], v[228:231], v[236:239], v[64:79]
	ds_read_b128 v[236:239], v191 offset:41536
	ds_write_b128 v249, v[128:131] offset:36864
	s_waitcnt lgkmcnt(9)
	v_mfma_f32_32x32x16_bf16 v[48:63], v[224:227], v[240:243], v[48:63]
	v_mfma_f32_32x32x16_bf16 v[32:47], v[228:231], v[240:243], v[32:47]
	ds_read_b128 v[240:243], v191 offset:46144
	ds_write_b128 v250, v[140:143]
	s_waitcnt lgkmcnt(9)
	v_mfma_f32_32x32x16_bf16 v[16:31], v[224:227], v[244:247], v[16:31]
	v_mfma_f32_32x32x16_bf16 v[0:15], v[228:231], v[244:247], v[0:15]
	ds_read_b128 v[244:247], v191 offset:50752
	ds_write_b128 v250, v[156:159] offset:36864
	ds_read_b128 v[224:227], v190 offset:96
	ds_read_b128 v[228:231], v190 offset:4704
	s_waitcnt lgkmcnt(9)
	v_mfma_f32_32x32x16_bf16 v[112:127], v[192:195], v[232:235], v[112:127]
	v_mfma_f32_32x32x16_bf16 v[96:111], v[220:223], v[232:235], v[96:111]
	ds_read_b128 v[232:235], v191 offset:36960
	v_add_u32_e32 v196, 0x12000, v196
	global_load_dwordx4 v[152:155], v[174:175], off
	v_lshl_add_u64 v[174:175], v[174:175], 0, s[58:59]
	s_waitcnt lgkmcnt(8)
	v_mfma_f32_32x32x16_bf16 v[80:95], v[192:195], v[236:239], v[80:95]
	v_mfma_f32_32x32x16_bf16 v[64:79], v[220:223], v[236:239], v[64:79]
	ds_read_b128 v[236:239], v191 offset:41568
	v_add_u32_e32 v197, 0x12000, v197
	global_load_dwordx4 v[136:139], v[166:167], off
	v_lshl_add_u64 v[166:167], v[166:167], 0, s[58:59]
	s_waitcnt lgkmcnt(7)
	v_mfma_f32_32x32x16_bf16 v[48:63], v[192:195], v[240:243], v[48:63]
	v_mfma_f32_32x32x16_bf16 v[32:47], v[220:223], v[240:243], v[32:47]
	ds_read_b128 v[240:243], v191 offset:46176
	v_add_u32_e32 v249, 0x12000, v249
	global_load_dwordx4 v[148:151], v[172:173], off
	v_lshl_add_u64 v[172:173], v[172:173], 0, s[58:59]
	s_waitcnt lgkmcnt(6)
	v_mfma_f32_32x32x16_bf16 v[16:31], v[192:195], v[244:247], v[16:31]
	v_mfma_f32_32x32x16_bf16 v[0:15], v[220:223], v[244:247], v[0:15]
	ds_read_b128 v[244:247], v191 offset:50784
	v_add_u32_e32 v250, 0x12000, v250
	global_load_dwordx4 v[132:135], v[164:165], off
	v_lshl_add_u64 v[164:165], v[164:165], 0, s[58:59]
	v_subrev_u32_e32 v190, 0x12000, v190
	v_subrev_u32_e32 v191, 0x12000, v191
	s_waitcnt lgkmcnt(3)
	v_mfma_f32_32x32x16_bf16 v[112:127], v[224:227], v[232:235], v[112:127]
	v_mfma_f32_32x32x16_bf16 v[96:111], v[228:231], v[232:235], v[96:111]
	global_load_dwordx4 v[144:147], v[170:171], off
	v_lshl_add_u64 v[170:171], v[170:171], 0, s[58:59]
	s_waitcnt lgkmcnt(2)
	v_mfma_f32_32x32x16_bf16 v[80:95], v[224:227], v[236:239], v[80:95]
	v_mfma_f32_32x32x16_bf16 v[64:79], v[228:231], v[236:239], v[64:79]
	global_load_dwordx4 v[128:131], v[162:163], off
	v_lshl_add_u64 v[162:163], v[162:163], 0, s[58:59]
	s_waitcnt lgkmcnt(1)
	v_mfma_f32_32x32x16_bf16 v[48:63], v[224:227], v[240:243], v[48:63]
	v_mfma_f32_32x32x16_bf16 v[32:47], v[228:231], v[240:243], v[32:47]
	global_load_dwordx4 v[140:143], v[168:169], off
	v_lshl_add_u64 v[168:169], v[168:169], 0, s[58:59]
	s_waitcnt lgkmcnt(0)
	v_mfma_f32_32x32x16_bf16 v[16:31], v[224:227], v[244:247], v[16:31]
	v_mfma_f32_32x32x16_bf16 v[0:15], v[228:231], v[244:247], v[0:15]
	global_load_dwordx4 v[156:159], v[160:161], off
	v_lshl_add_u64 v[160:161], v[160:161], 0, s[58:59]
	s_waitcnt lgkmcnt(0)
	s_barrier
	s_add_i32 s64, s64, -1
	s_cmp_lg_u32 s64, 0
	s_cbranch_scc1 .Lgn_loop
; template <bool AT>
; DI void gemm_main(f32x16 (&acc)[2][4], const u16* __restrict__ R, int ldr, const u16* __restrict__ Cm, int ldc,
;                   const u16* __restrict__ RT, int ldrt, int K, char* smem, int tid) {
;     ...
;   for (int kt = -1; kt < nk; ++kt) {
;     if (kt + 1 < nk) {
;       const int ks1 = kt + 1;
;       u16* Rs = S0 + (ks1 & 1) * STG;
;       u16* Cs = Rs + 256 * 72;
; #pragma unroll
;       for (int i = 0; i < 4; ++i) {
;         const int cid = tid + NT * i;
;         const int row = cid >> 3, kc = cid & 7;
;         if (AT && ks1 < 8) {
;           const int kr = cid >> 5, tc = cid & 31;
;           *(u32x4*)(Rs + kr * 264 + tc * 8) = rr[i];
;         } else {
;           *(u32x4*)(Rs + row * 72 + kc * 8) = rr[i];
;         }
;         *(u32x4*)(Cs + row * 72 + kc * 8) = cr[i];
;       }
;     }
;     if (kt + 2 < nk) {
;       const int kn = kt + 2;
; #pragma unroll
;       for (int i = 0; i < 4; ++i) {
;         const int cid = tid + NT * i;
;         const int row = cid >> 3, kc = cid & 7;
;         if (AT && kn < 8) {
;           const int kr = cid >> 5, tc = cid & 31;
;           rr[i] = *(const u32x4*)(RT + (size_t)(kn * 64 + kr) * ldrt + tc * 8);
;         } else {
;           rr[i] = *(const u32x4*)(R + (size_t)row * ldr + kn * 64 + kc * 8);
;         }
;         cr[i] = *(const u32x4*)(Cm + (size_t)row * ldc + kn * 64 + kc * 8);
;       }
;     }
;     __builtin_amdgcn_sched_barrier(0x38F);
;     if (kt >= 0) {
;       const u16* Rs = S0 + (kt & 1) * STG;
;       const u16* Cs = Rs + 256 * 72;
;       const u16* RTs = Rs;
; #pragma unroll
;       for (int ks = 0; ks < 4; ++ks) {
;         bf16x8 rf[2];
; #pragma unroll
;         for (int rb = 0; rb < 2; ++rb) {
;           if (AT && kt < 8) {
;             const u16* src = RTs + (16 * ks + 8 * g) * 264 + 64 * wr + 32 * rb + li;
;             bf16x8 t;
; #pragma unroll
;             for (int j = 0; j < 8; ++j) t[j] = (short)src[j * 264];
;             rf[rb] = t;
;           } else {
;             rf[rb] = *(const bf16x8*)(Rs + (64 * wr + 32 * rb + li) * 72 + 16 * ks + 8 * g);
;           }
;         }
; #pragma unroll
;         for (int cb = 0; cb < 4; ++cb) {
;           const bf16x8 cfv = *(const bf16x8*)(Cs + (128 * wc + 32 * cb + li) * 72 + 16 * ks + 8 * g);
; #pragma unroll
;           for (int rb = 0; rb < 2; ++rb) acc[rb][cb] = MFMA(rf[rb], cfv, acc[rb][cb]);
	ds_read_b128 v[192:195], v190 offset:0
	ds_read_b128 v[220:223], v190 offset:4608
	ds_read_b128 v[232:235], v191 offset:36864
	ds_read_b128 v[236:239], v191 offset:41472
	ds_read_b128 v[240:243], v191 offset:46080
	ds_read_b128 v[244:247], v191 offset:50688
	ds_read_b128 v[224:227], v190 offset:32
	ds_read_b128 v[228:231], v190 offset:4640
	s_waitcnt lgkmcnt(5)
	v_mfma_f32_32x32x16_bf16 v[112:127], v[192:195], v[232:235], v[112:127]
	v_mfma_f32_32x32x16_bf16 v[96:111], v[220:223], v[232:235], v[96:111]
	ds_read_b128 v[232:235], v191 offset:36896
	s_waitcnt vmcnt(0)
	ds_write_b128 v196, v[152:155]
	s_waitcnt lgkmcnt(6)
	v_mfma_f32_32x32x16_bf16 v[80:95], v[192:195], v[236:239], v[80:95]
	v_mfma_f32_32x32x16_bf16 v[64:79], v[220:223], v[236:239], v[64:79]
	ds_read_b128 v[236:239], v191 offset:41504
	ds_write_b128 v196, v[136:139] offset:36864
	s_waitcnt lgkmcnt(7)
	v_mfma_f32_32x32x16_bf16 v[48:63], v[192:195], v[240:243], v[48:63]
	v_mfma_f32_32x32x16_bf16 v[32:47], v[220:223], v[240:243], v[32:47]
	ds_read_b128 v[240:243], v191 offset:46112
	ds_write_b128 v197, v[148:151]
	s_waitcnt lgkmcnt(8)
	v_mfma_f32_32x32x16_bf16 v[16:31], v[192:195], v[244:247], v[16:31]
	v_mfma_f32_32x32x16_bf16 v[0:15], v[220:223], v[244:247], v[0:15]
	ds_read_b128 v[244:247], v191 offset:50720
	ds_write_b128 v197, v[132:135] offset:36864
	ds_read_b128 v[192:195], v190 offset:64
	ds_read_b128 v[220:223], v190 offset:4672
	s_waitcnt lgkmcnt(9)
	v_mfma_f32_32x32x16_bf16 v[112:127], v[224:227], v[232:235], v[112:127]
	v_mfma_f32_32x32x16_bf16 v[96:111], v[228:231], v[232:235], v[96:111]
	ds_read_b128 v[232:235], v191 offset:36928
	ds_write_b128 v249, v[144:147]
	s_waitcnt lgkmcnt(9)
	v_mfma_f32_32x32x16_bf16 v[80:95], v[224:227], v[236:239], v[80:95]
	v_mfma_f32_32x32x16_bf16 v[64:79], v[228:231], v[236:239], v[64:79]
	ds_read_b128 v[236:239], v191 offset:41536
	ds_write_b128 v249, v[128:131] offset:36864
	s_waitcnt lgkmcnt(9)
	v_mfma_f32_32x32x16_bf16 v[48:63], v[224:227], v[240:243], v[48:63]
	v_mfma_f32_32x32x16_bf16 v[32:47], v[228:231], v[240:243], v[32:47]
	ds_read_b128 v[240:243], v191 offset:46144
	ds_write_b128 v250, v[140:143]
	s_waitcnt lgkmcnt(9)
	v_mfma_f32_32x32x16_bf16 v[16:31], v[224:227], v[244:247], v[16:31]
	v_mfma_f32_32x32x16_bf16 v[0:15], v[228:231], v[244:247], v[0:15]
	ds_read_b128 v[244:247], v191 offset:50752
	ds_write_b128 v250, v[156:159] offset:36864
	ds_read_b128 v[224:227], v190 offset:96
	ds_read_b128 v[228:231], v190 offset:4704
	s_waitcnt lgkmcnt(9)
	v_mfma_f32_32x32x16_bf16 v[112:127], v[192:195], v[232:235], v[112:127]
	v_mfma_f32_32x32x16_bf16 v[96:111], v[220:223], v[232:235], v[96:111]
	ds_read_b128 v[232:235], v191 offset:36960
	v_subrev_u32_e32 v196, 0x12000, v196
	s_waitcnt lgkmcnt(8)
	v_mfma_f32_32x32x16_bf16 v[80:95], v[192:195], v[236:239], v[80:95]
	v_mfma_f32_32x32x16_bf16 v[64:79], v[220:223], v[236:239], v[64:79]
	ds_read_b128 v[236:239], v191 offset:41568
	v_subrev_u32_e32 v197, 0x12000, v197
	s_waitcnt lgkmcnt(7)
	v_mfma_f32_32x32x16_bf16 v[48:63], v[192:195], v[240:243], v[48:63]
	v_mfma_f32_32x32x16_bf16 v[32:47], v[220:223], v[240:243], v[32:47]
	ds_read_b128 v[240:243], v191 offset:46176
	v_subrev_u32_e32 v249, 0x12000, v249
	s_waitcnt lgkmcnt(6)
	v_mfma_f32_32x32x16_bf16 v[16:31], v[192:195], v[244:247], v[16:31]
	v_mfma_f32_32x32x16_bf16 v[0:15], v[220:223], v[244:247], v[0:15]
	ds_read_b128 v[244:247], v191 offset:50784
	v_subrev_u32_e32 v250, 0x12000, v250
	v_add_u32_e32 v190, 0x12000, v190
	v_add_u32_e32 v191, 0x12000, v191
	s_waitcnt lgkmcnt(3)
	v_mfma_f32_32x32x16_bf16 v[112:127], v[224:227], v[232:235], v[112:127]
	v_mfma_f32_32x32x16_bf16 v[96:111], v[228:231], v[232:235], v[96:111]
	s_waitcnt lgkmcnt(2)
	v_mfma_f32_32x32x16_bf16 v[80:95], v[224:227], v[236:239], v[80:95]
	v_mfma_f32_32x32x16_bf16 v[64:79], v[228:231], v[236:239], v[64:79]
	s_waitcnt lgkmcnt(1)
	v_mfma_f32_32x32x16_bf16 v[48:63], v[224:227], v[240:243], v[48:63]
	v_mfma_f32_32x32x16_bf16 v[32:47], v[228:231], v[240:243], v[32:47]
	s_waitcnt lgkmcnt(0)
	v_mfma_f32_32x32x16_bf16 v[16:31], v[224:227], v[244:247], v[16:31]
	v_mfma_f32_32x32x16_bf16 v[0:15], v[228:231], v[244:247], v[0:15]
	s_waitcnt lgkmcnt(0)
	s_barrier
	ds_read_b128 v[192:195], v190 offset:0
	ds_read_b128 v[220:223], v190 offset:4608
	ds_read_b128 v[232:235], v191 offset:36864
	ds_read_b128 v[236:239], v191 offset:41472
	ds_read_b128 v[240:243], v191 offset:46080
	ds_read_b128 v[244:247], v191 offset:50688
	ds_read_b128 v[224:227], v190 offset:32
	ds_read_b128 v[228:231], v190 offset:4640
	s_waitcnt lgkmcnt(5)
	v_mfma_f32_32x32x16_bf16 v[112:127], v[192:195], v[232:235], v[112:127]
	v_mfma_f32_32x32x16_bf16 v[96:111], v[220:223], v[232:235], v[96:111]
	ds_read_b128 v[232:235], v191 offset:36896
	s_waitcnt lgkmcnt(5)
	v_mfma_f32_32x32x16_bf16 v[80:95], v[192:195], v[236:239], v[80:95]
	v_mfma_f32_32x32x16_bf16 v[64:79], v[220:223], v[236:239], v[64:79]
	ds_read_b128 v[236:239], v191 offset:41504
	s_waitcnt lgkmcnt(5)
	v_mfma_f32_32x32x16_bf16 v[48:63], v[192:195], v[240:243], v[48:63]
	v_mfma_f32_32x32x16_bf16 v[32:47], v[220:223], v[240:243], v[32:47]
	ds_read_b128 v[240:243], v191 offset:46112
	s_waitcnt lgkmcnt(5)
	v_mfma_f32_32x32x16_bf16 v[16:31], v[192:195], v[244:247], v[16:31]
	v_mfma_f32_32x32x16_bf16 v[0:15], v[220:223], v[244:247], v[0:15]
	ds_read_b128 v[244:247], v191 offset:50720
	ds_read_b128 v[192:195], v190 offset:64
	ds_read_b128 v[220:223], v190 offset:4672
	s_waitcnt lgkmcnt(5)
	v_mfma_f32_32x32x16_bf16 v[112:127], v[224:227], v[232:235], v[112:127]
	v_mfma_f32_32x32x16_bf16 v[96:111], v[228:231], v[232:235], v[96:111]
	ds_read_b128 v[232:235], v191 offset:36928
	s_waitcnt lgkmcnt(5)
; template <bool AT>
; DI void gemm_main(f32x16 (&acc)[2][4], const u16* __restrict__ R, int ldr, const u16* __restrict__ Cm, int ldc,
;                   const u16* __restrict__ RT, int ldrt, int K, char* smem, int tid) {
;     ...
;   for (int kt = -1; kt < nk; ++kt) {
;     if (kt + 1 < nk) {
;       const int ks1 = kt + 1;
;       u16* Rs = S0 + (ks1 & 1) * STG;
;       u16* Cs = Rs + 256 * 72;
; #pragma unroll
;       for (int i = 0; i < 4; ++i) {
;         const int cid = tid + NT * i;
;         const int row = cid >> 3, kc = cid & 7;
;         if (AT && ks1 < 8) {
;           const int kr = cid >> 5, tc = cid & 31;
;           *(u32x4*)(Rs + kr * 264 + tc * 8) = rr[i];
;         } else {
;           *(u32x4*)(Rs + row * 72 + kc * 8) = rr[i];
;         }
;         *(u32x4*)(Cs + row * 72 + kc * 8) = cr[i];
;       }
;     }
;     if (kt + 2 < nk) {
;       const int kn = kt + 2;
; #pragma unroll
;       for (int i = 0; i < 4; ++i) {
;         const int cid = tid + NT * i;
;         const int row = cid >> 3, kc = cid & 7;
;         if (AT && kn < 8) {
;           const int kr = cid >> 5, tc = cid & 31;
;           rr[i] = *(const u32x4*)(RT + (size_t)(kn * 64 + kr) * ldrt + tc * 8);
;         } else {
;           rr[i] = *(const u32x4*)(R + (size_t)row * ldr + kn * 64 + kc * 8);
;         }
;         cr[i] = *(const u32x4*)(Cm + (size_t)row * ldc + kn * 64 + kc * 8);
;       }
;     }
;     __builtin_amdgcn_sched_barrier(0x38F);
;     if (kt >= 0) {
;       const u16* Rs = S0 + (kt & 1) * STG;
;       const u16* Cs = Rs + 256 * 72;
;       const u16* RTs = Rs;
; #pragma unroll
;       for (int ks = 0; ks < 4; ++ks) {
;         bf16x8 rf[2];
; #pragma unroll
;         for (int rb = 0; rb < 2; ++rb) {
;           if (AT && kt < 8) {
;             const u16* src = RTs + (16 * ks + 8 * g) * 264 + 64 * wr + 32 * rb + li;
;             bf16x8 t;
; #pragma unroll
;             for (int j = 0; j < 8; ++j) t[j] = (short)src[j * 264];
;             rf[rb] = t;
;           } else {
;             rf[rb] = *(const bf16x8*)(Rs + (64 * wr + 32 * rb + li) * 72 + 16 * ks + 8 * g);
;           }
;         }
; #pragma unroll
;         for (int cb = 0; cb < 4; ++cb) {
;           const bf16x8 cfv = *(const bf16x8*)(Cs + (128 * wc + 32 * cb + li) * 72 + 16 * ks + 8 * g);
; #pragma unroll
;           for (int rb = 0; rb < 2; ++rb) acc[rb][cb] = MFMA(rf[rb], cfv, acc[rb][cb]);
	v_mfma_f32_32x32x16_bf16 v[80:95], v[224:227], v[236:239], v[80:95]
	v_mfma_f32_32x32x16_bf16 v[64:79], v[228:231], v[236:239], v[64:79]
	ds_read_b128 v[236:239], v191 offset:41536
	s_waitcnt lgkmcnt(5)
	v_mfma_f32_32x32x16_bf16 v[48:63], v[224:227], v[240:243], v[48:63]
	v_mfma_f32_32x32x16_bf16 v[32:47], v[228:231], v[240:243], v[32:47]
	ds_read_b128 v[240:243], v191 offset:46144
	s_waitcnt lgkmcnt(5)
	v_mfma_f32_32x32x16_bf16 v[16:31], v[224:227], v[244:247], v[16:31]
	v_mfma_f32_32x32x16_bf16 v[0:15], v[228:231], v[244:247], v[0:15]
	ds_read_b128 v[244:247], v191 offset:50752
	ds_read_b128 v[224:227], v190 offset:96
	ds_read_b128 v[228:231], v190 offset:4704
	s_waitcnt lgkmcnt(5)
	v_mfma_f32_32x32x16_bf16 v[112:127], v[192:195], v[232:235], v[112:127]
	v_mfma_f32_32x32x16_bf16 v[96:111], v[220:223], v[232:235], v[96:111]
	ds_read_b128 v[232:235], v191 offset:36960
	v_add_u32_e32 v196, 0x12000, v196
	s_waitcnt lgkmcnt(5)
	v_mfma_f32_32x32x16_bf16 v[80:95], v[192:195], v[236:239], v[80:95]
	v_mfma_f32_32x32x16_bf16 v[64:79], v[220:223], v[236:239], v[64:79]
	ds_read_b128 v[236:239], v191 offset:41568
	v_add_u32_e32 v197, 0x12000, v197
	s_waitcnt lgkmcnt(5)
	v_mfma_f32_32x32x16_bf16 v[48:63], v[192:195], v[240:243], v[48:63]
	v_mfma_f32_32x32x16_bf16 v[32:47], v[220:223], v[240:243], v[32:47]
	ds_read_b128 v[240:243], v191 offset:46176
	v_add_u32_e32 v249, 0x12000, v249
	s_waitcnt lgkmcnt(5)
	v_mfma_f32_32x32x16_bf16 v[16:31], v[192:195], v[244:247], v[16:31]
	v_mfma_f32_32x32x16_bf16 v[0:15], v[220:223], v[244:247], v[0:15]
	ds_read_b128 v[244:247], v191 offset:50784
	v_add_u32_e32 v250, 0x12000, v250
	v_subrev_u32_e32 v190, 0x12000, v190
	v_subrev_u32_e32 v191, 0x12000, v191
	s_waitcnt lgkmcnt(3)
	v_mfma_f32_32x32x16_bf16 v[112:127], v[224:227], v[232:235], v[112:127]
	v_mfma_f32_32x32x16_bf16 v[96:111], v[228:231], v[232:235], v[96:111]
	s_waitcnt lgkmcnt(2)
	v_mfma_f32_32x32x16_bf16 v[80:95], v[224:227], v[236:239], v[80:95]
	v_mfma_f32_32x32x16_bf16 v[64:79], v[228:231], v[236:239], v[64:79]
	s_waitcnt lgkmcnt(1)
	v_mfma_f32_32x32x16_bf16 v[48:63], v[224:227], v[240:243], v[48:63]
	v_mfma_f32_32x32x16_bf16 v[32:47], v[228:231], v[240:243], v[32:47]
	s_waitcnt lgkmcnt(0)
	v_mfma_f32_32x32x16_bf16 v[16:31], v[224:227], v[244:247], v[16:31]
	v_mfma_f32_32x32x16_bf16 v[0:15], v[228:231], v[244:247], v[0:15]
	s_waitcnt lgkmcnt(0)
	s_barrier
	s_nop 7
	v_mov_b32_e32 v162, s56
	s_lshl_b32 s9, s75, 4
	s_and_b32 s9, s9, 0x200
	s_add_i32 s9, s8, s9
	s_addk_i32 s9, 0xf400
	v_lshrrev_b32_e32 v128, 3, v177
	v_and_b32_e32 v163, 4, v128
	v_add_u32_e32 v130, s9, v178
	s_movk_i32 s9, 0x4080
	v_add_u32_e32 v132, s8, v178
	s_add_i32 s8, 0, 0x24000
	v_lshl_add_u32 v128, v176, 2, s8
	ds_read_b32 v164, v128
	v_mov_b64_e32 v[128:129], s[28:29]
	v_mad_i64_i32 v[128:129], s[10:11], v130, s9, v[128:129]
	s_movk_i32 s9, 0x1f9f
	v_or_b32_e32 v133, s56, v176
	v_bitop3_b32 v134, v176, s9, v162 bitop3:0xc8
	v_mov_b64_e32 v[130:131], s[38:39]
	s_and_b64 s[10:11], s[6:7], exec
	s_movk_i32 s9, 0x4040
	v_mad_i64_i32 v[130:131], s[10:11], v132, s67, v[130:131]
	v_cndmask_b32_e64 v132, v134, v133, s[6:7]
	s_cselect_b32 s9, s9, 0x2040
	v_cndmask_b32_e64 v129, v129, v131, s[6:7]
	v_cndmask_b32_e64 v128, v128, v130, s[6:7]
	v_lshlrev_b32_e32 v188, 1, v132
	v_mul_u32_u24_e32 v130, s9, v163
	v_lshl_add_u64 v[138:139], v[128:129], 0, v[188:189]
	v_readfirstlane_b32 s98, v138
	v_readfirstlane_b32 s99, v139
	s_lshl_b32 s100, s9, 1
	s_lshl_b32 s101, s9, 3
	v_and_b32_e32 v144, 63, v198
	v_lshrrev_b32_e32 v145, 6, v198
	v_mul_u32_u24_e32 v145, 0x4400, v145
	v_lshrrev_b32_e32 v146, 5, v144
	v_mul_u32_u24_e32 v146, 0x440, v146
	v_and_b32_e32 v147, 31, v144
	v_lshl_add_u32 v148, v147, 1, v146
	v_add_u32_e32 v148, v148, v145
	v_lshrrev_b32_e32 v146, 4, v144
	v_and_b32_e32 v147, 15, v144
	v_mul_u32_u24_e32 v149, 0x110, v146
	v_lshl_add_u32 v149, v147, 4, v149
	v_add_u32_e32 v149, v149, v145
	v_mul_lo_u32 v150, v146, s100
	v_lshl_add_u32 v150, v147, 4, v150
	v_lshl_add_u32 v151, v176, 2, s8
	ds_read_b32 v140, v151 offset:0
	ds_read_b32 v141, v151 offset:128
	ds_read_b32 v142, v151 offset:256
	ds_read_b32 v143, v151 offset:384
	s_waitcnt lgkmcnt(0)
	v_mul_f32_e32 v112, v112, v140
	v_mul_f32_e32 v113, v113, v140
	v_cvt_pk_bf16_f32 v152, v112, v113
	ds_write_b16 v148, v152 offset:0
	v_lshrrev_b32_e32 v152, 16, v152
	ds_write_b16 v148, v152 offset:272
	v_mul_f32_e32 v114, v114, v140
	v_mul_f32_e32 v115, v115, v140
	v_cvt_pk_bf16_f32 v153, v114, v115
	ds_write_b16 v148, v153 offset:544
	v_lshrrev_b32_e32 v153, 16, v153
	ds_write_b16 v148, v153 offset:816
	v_mul_f32_e32 v116, v116, v140
	v_mul_f32_e32 v117, v117, v140
	v_cvt_pk_bf16_f32 v154, v116, v117
	ds_write_b16 v148, v154 offset:2176
	v_lshrrev_b32_e32 v154, 16, v154
	ds_write_b16 v148, v154 offset:2448
	v_mul_f32_e32 v118, v118, v140
	v_mul_f32_e32 v119, v119, v140
	v_cvt_pk_bf16_f32 v155, v118, v119
	ds_write_b16 v148, v155 offset:2720
	v_lshrrev_b32_e32 v155, 16, v155
	ds_write_b16 v148, v155 offset:2992
	v_mul_f32_e32 v120, v120, v140
	v_mul_f32_e32 v121, v121, v140
	v_cvt_pk_bf16_f32 v156, v120, v121
	ds_write_b16 v148, v156 offset:4352
	v_lshrrev_b32_e32 v156, 16, v156
	ds_write_b16 v148, v156 offset:4624
	v_mul_f32_e32 v122, v122, v140
	v_mul_f32_e32 v123, v123, v140
	v_cvt_pk_bf16_f32 v157, v122, v123
	ds_write_b16 v148, v157 offset:4896
	v_lshrrev_b32_e32 v157, 16, v157
	ds_write_b16 v148, v157 offset:5168
	v_mul_f32_e32 v124, v124, v140
	v_mul_f32_e32 v125, v125, v140
	v_cvt_pk_bf16_f32 v158, v124, v125
	ds_write_b16 v148, v158 offset:6528
	v_lshrrev_b32_e32 v158, 16, v158
	ds_write_b16 v148, v158 offset:6800
; DI u16 f2bf(float a) { return (u16)(pack2(a, 0.f) & 0xffffu); }
; DI int crow(int reg, int g) { return (reg & 3) + 8 * (reg >> 2) + 4 * g; }
; template <bool TR>
; DI void gemm_in_tile(const P& p, int l, int id, char* smem) {
;     ...
;     for (int cb = 0; cb < 4; ++cb) {
;       asm volatile("" ::: "memory");
;       const int tl = 128 * wc + 32 * cb + li;
;       const int tok = m0 + tl;
;       const float rs = rs_s[tl];
;       u16* dst = hy ? (p.hyT + (size_t)(n0 + 64 * wr) * HYP + tok)
;                     : (p.VT + (size_t)((tok >> 13) * 512 + (n0 - 3072) + 64 * wr) * VTP + (tok & 8191));
;       const size_t cstride = hy ? (size_t)HYP : (size_t)VTP;
; #pragma unroll
;       for (int rb = 0; rb < 2; ++rb) {
; #pragma unroll
;         for (int reg = 0; reg < 16; ++reg) {
;           const int cl = 32 * rb + crow(reg, g);
;           dst[(size_t)cl * cstride] = f2bf(acc[rb][cb][reg] * rs);
;         }
;       }
	v_mul_f32_e32 v126, v126, v140
	v_mul_f32_e32 v127, v127, v140
	v_cvt_pk_bf16_f32 v159, v126, v127
	ds_write_b16 v148, v159 offset:7072
	v_lshrrev_b32_e32 v159, 16, v159
	ds_write_b16 v148, v159 offset:7344
	v_mul_f32_e32 v96, v96, v140
	v_mul_f32_e32 v97, v97, v140
	v_cvt_pk_bf16_f32 v152, v96, v97
	ds_write_b16 v148, v152 offset:8704
	v_lshrrev_b32_e32 v152, 16, v152
	ds_write_b16 v148, v152 offset:8976
	v_mul_f32_e32 v98, v98, v140
	v_mul_f32_e32 v99, v99, v140
	v_cvt_pk_bf16_f32 v153, v98, v99
	ds_write_b16 v148, v153 offset:9248
	v_lshrrev_b32_e32 v153, 16, v153
	ds_write_b16 v148, v153 offset:9520
	v_mul_f32_e32 v100, v100, v140
	v_mul_f32_e32 v101, v101, v140
	v_cvt_pk_bf16_f32 v154, v100, v101
	ds_write_b16 v148, v154 offset:10880
	v_lshrrev_b32_e32 v154, 16, v154
	ds_write_b16 v148, v154 offset:11152
	v_mul_f32_e32 v102, v102, v140
	v_mul_f32_e32 v103, v103, v140
	v_cvt_pk_bf16_f32 v155, v102, v103
	ds_write_b16 v148, v155 offset:11424
	v_lshrrev_b32_e32 v155, 16, v155
	ds_write_b16 v148, v155 offset:11696
	v_mul_f32_e32 v104, v104, v140
	v_mul_f32_e32 v105, v105, v140
	v_cvt_pk_bf16_f32 v156, v104, v105
	ds_write_b16 v148, v156 offset:13056
	v_lshrrev_b32_e32 v156, 16, v156
	ds_write_b16 v148, v156 offset:13328
	v_mul_f32_e32 v106, v106, v140
	v_mul_f32_e32 v107, v107, v140
	v_cvt_pk_bf16_f32 v157, v106, v107
	ds_write_b16 v148, v157 offset:13600
	v_lshrrev_b32_e32 v157, 16, v157
	ds_write_b16 v148, v157 offset:13872
	v_mul_f32_e32 v108, v108, v140
	v_mul_f32_e32 v109, v109, v140
	v_cvt_pk_bf16_f32 v158, v108, v109
	ds_write_b16 v148, v158 offset:15232
	v_lshrrev_b32_e32 v158, 16, v158
	ds_write_b16 v148, v158 offset:15504
	v_mul_f32_e32 v110, v110, v140
	v_mul_f32_e32 v111, v111, v140
	v_cvt_pk_bf16_f32 v159, v110, v111
	ds_write_b16 v148, v159 offset:15776
	v_lshrrev_b32_e32 v159, 16, v159
	ds_write_b16 v148, v159 offset:16048
	v_mul_f32_e32 v80, v80, v141
	v_mul_f32_e32 v81, v81, v141
	v_cvt_pk_bf16_f32 v152, v80, v81
	ds_write_b16 v148, v152 offset:64
	v_lshrrev_b32_e32 v152, 16, v152
	ds_write_b16 v148, v152 offset:336
	v_mul_f32_e32 v82, v82, v141
	v_mul_f32_e32 v83, v83, v141
	v_cvt_pk_bf16_f32 v153, v82, v83
	ds_write_b16 v148, v153 offset:608
	v_lshrrev_b32_e32 v153, 16, v153
	ds_write_b16 v148, v153 offset:880
	v_mul_f32_e32 v84, v84, v141
	v_mul_f32_e32 v85, v85, v141
	v_cvt_pk_bf16_f32 v154, v84, v85
	ds_write_b16 v148, v154 offset:2240
	v_lshrrev_b32_e32 v154, 16, v154
	ds_write_b16 v148, v154 offset:2512
	v_mul_f32_e32 v86, v86, v141
	v_mul_f32_e32 v87, v87, v141
	v_cvt_pk_bf16_f32 v155, v86, v87
	ds_write_b16 v148, v155 offset:2784
	v_lshrrev_b32_e32 v155, 16, v155
	ds_write_b16 v148, v155 offset:3056
	v_mul_f32_e32 v88, v88, v141
	v_mul_f32_e32 v89, v89, v141
	v_cvt_pk_bf16_f32 v156, v88, v89
	ds_write_b16 v148, v156 offset:4416
	v_lshrrev_b32_e32 v156, 16, v156
	ds_write_b16 v148, v156 offset:4688
	v_mul_f32_e32 v90, v90, v141
	v_mul_f32_e32 v91, v91, v141
	v_cvt_pk_bf16_f32 v157, v90, v91
	ds_write_b16 v148, v157 offset:4960
	v_lshrrev_b32_e32 v157, 16, v157
	ds_write_b16 v148, v157 offset:5232
	v_mul_f32_e32 v92, v92, v141
	v_mul_f32_e32 v93, v93, v141
	v_cvt_pk_bf16_f32 v158, v92, v93
	ds_write_b16 v148, v158 offset:6592
	v_lshrrev_b32_e32 v158, 16, v158
	ds_write_b16 v148, v158 offset:6864
	v_mul_f32_e32 v94, v94, v141
	v_mul_f32_e32 v95, v95, v141
	v_cvt_pk_bf16_f32 v159, v94, v95
	ds_write_b16 v148, v159 offset:7136
	v_lshrrev_b32_e32 v159, 16, v159
	ds_write_b16 v148, v159 offset:7408
	v_mul_f32_e32 v64, v64, v141
	v_mul_f32_e32 v65, v65, v141
	v_cvt_pk_bf16_f32 v152, v64, v65
	ds_write_b16 v148, v152 offset:8768
	v_lshrrev_b32_e32 v152, 16, v152
	ds_write_b16 v148, v152 offset:9040
	v_mul_f32_e32 v66, v66, v141
	v_mul_f32_e32 v67, v67, v141
	v_cvt_pk_bf16_f32 v153, v66, v67
	ds_write_b16 v148, v153 offset:9312
	v_lshrrev_b32_e32 v153, 16, v153
	ds_write_b16 v148, v153 offset:9584
	v_mul_f32_e32 v68, v68, v141
	v_mul_f32_e32 v69, v69, v141
	v_cvt_pk_bf16_f32 v154, v68, v69
	ds_write_b16 v148, v154 offset:10944
	v_lshrrev_b32_e32 v154, 16, v154
	ds_write_b16 v148, v154 offset:11216
	v_mul_f32_e32 v70, v70, v141
	v_mul_f32_e32 v71, v71, v141
	v_cvt_pk_bf16_f32 v155, v70, v71
	ds_write_b16 v148, v155 offset:11488
	v_lshrrev_b32_e32 v155, 16, v155
	ds_write_b16 v148, v155 offset:11760
	v_mul_f32_e32 v72, v72, v141
	v_mul_f32_e32 v73, v73, v141
	v_cvt_pk_bf16_f32 v156, v72, v73
	ds_write_b16 v148, v156 offset:13120
	v_lshrrev_b32_e32 v156, 16, v156
	ds_write_b16 v148, v156 offset:13392
	v_mul_f32_e32 v74, v74, v141
	v_mul_f32_e32 v75, v75, v141
	v_cvt_pk_bf16_f32 v157, v74, v75
	ds_write_b16 v148, v157 offset:13664
	v_lshrrev_b32_e32 v157, 16, v157
	ds_write_b16 v148, v157 offset:13936
	v_mul_f32_e32 v76, v76, v141
	v_mul_f32_e32 v77, v77, v141
	v_cvt_pk_bf16_f32 v158, v76, v77
	ds_write_b16 v148, v158 offset:15296
	v_lshrrev_b32_e32 v158, 16, v158
	ds_write_b16 v148, v158 offset:15568
	v_mul_f32_e32 v78, v78, v141
	v_mul_f32_e32 v79, v79, v141
	v_cvt_pk_bf16_f32 v159, v78, v79
	ds_write_b16 v148, v159 offset:15840
	v_lshrrev_b32_e32 v159, 16, v159
	ds_write_b16 v148, v159 offset:16112
	v_mul_f32_e32 v48, v48, v142
	v_mul_f32_e32 v49, v49, v142
	v_cvt_pk_bf16_f32 v152, v48, v49
	ds_write_b16 v148, v152 offset:128
	v_lshrrev_b32_e32 v152, 16, v152
	ds_write_b16 v148, v152 offset:400
	v_mul_f32_e32 v50, v50, v142
	v_mul_f32_e32 v51, v51, v142
	v_cvt_pk_bf16_f32 v153, v50, v51
	ds_write_b16 v148, v153 offset:672
	v_lshrrev_b32_e32 v153, 16, v153
	ds_write_b16 v148, v153 offset:944
	v_mul_f32_e32 v52, v52, v142
	v_mul_f32_e32 v53, v53, v142
	v_cvt_pk_bf16_f32 v154, v52, v53
	ds_write_b16 v148, v154 offset:2304
; DI u16 f2bf(float a) { return (u16)(pack2(a, 0.f) & 0xffffu); }
; DI int crow(int reg, int g) { return (reg & 3) + 8 * (reg >> 2) + 4 * g; }
; template <bool TR>
; DI void gemm_in_tile(const P& p, int l, int id, char* smem) {
;     ...
;     for (int cb = 0; cb < 4; ++cb) {
;       asm volatile("" ::: "memory");
;       const int tl = 128 * wc + 32 * cb + li;
;       const int tok = m0 + tl;
;       const float rs = rs_s[tl];
;       u16* dst = hy ? (p.hyT + (size_t)(n0 + 64 * wr) * HYP + tok)
;                     : (p.VT + (size_t)((tok >> 13) * 512 + (n0 - 3072) + 64 * wr) * VTP + (tok & 8191));
;       const size_t cstride = hy ? (size_t)HYP : (size_t)VTP;
; #pragma unroll
;       for (int rb = 0; rb < 2; ++rb) {
; #pragma unroll
;         for (int reg = 0; reg < 16; ++reg) {
;           const int cl = 32 * rb + crow(reg, g);
;           dst[(size_t)cl * cstride] = f2bf(acc[rb][cb][reg] * rs);
;         }
;       }
	v_lshrrev_b32_e32 v154, 16, v154
	ds_write_b16 v148, v154 offset:2576
	v_mul_f32_e32 v54, v54, v142
	v_mul_f32_e32 v55, v55, v142
	v_cvt_pk_bf16_f32 v155, v54, v55
	ds_write_b16 v148, v155 offset:2848
	v_lshrrev_b32_e32 v155, 16, v155
	ds_write_b16 v148, v155 offset:3120
	v_mul_f32_e32 v56, v56, v142
	v_mul_f32_e32 v57, v57, v142
	v_cvt_pk_bf16_f32 v156, v56, v57
	ds_write_b16 v148, v156 offset:4480
	v_lshrrev_b32_e32 v156, 16, v156
	ds_write_b16 v148, v156 offset:4752
	v_mul_f32_e32 v58, v58, v142
	v_mul_f32_e32 v59, v59, v142
	v_cvt_pk_bf16_f32 v157, v58, v59
	ds_write_b16 v148, v157 offset:5024
	v_lshrrev_b32_e32 v157, 16, v157
	ds_write_b16 v148, v157 offset:5296
	v_mul_f32_e32 v60, v60, v142
	v_mul_f32_e32 v61, v61, v142
	v_cvt_pk_bf16_f32 v158, v60, v61
	ds_write_b16 v148, v158 offset:6656
	v_lshrrev_b32_e32 v158, 16, v158
	ds_write_b16 v148, v158 offset:6928
	v_mul_f32_e32 v62, v62, v142
	v_mul_f32_e32 v63, v63, v142
	v_cvt_pk_bf16_f32 v159, v62, v63
	ds_write_b16 v148, v159 offset:7200
	v_lshrrev_b32_e32 v159, 16, v159
	ds_write_b16 v148, v159 offset:7472
	v_mul_f32_e32 v32, v32, v142
	v_mul_f32_e32 v33, v33, v142
	v_cvt_pk_bf16_f32 v152, v32, v33
	ds_write_b16 v148, v152 offset:8832
	v_lshrrev_b32_e32 v152, 16, v152
	ds_write_b16 v148, v152 offset:9104
	v_mul_f32_e32 v34, v34, v142
	v_mul_f32_e32 v35, v35, v142
	v_cvt_pk_bf16_f32 v153, v34, v35
	ds_write_b16 v148, v153 offset:9376
	v_lshrrev_b32_e32 v153, 16, v153
	ds_write_b16 v148, v153 offset:9648
	v_mul_f32_e32 v36, v36, v142
	v_mul_f32_e32 v37, v37, v142
	v_cvt_pk_bf16_f32 v154, v36, v37
	ds_write_b16 v148, v154 offset:11008
	v_lshrrev_b32_e32 v154, 16, v154
	ds_write_b16 v148, v154 offset:11280
	v_mul_f32_e32 v38, v38, v142
	v_mul_f32_e32 v39, v39, v142
	v_cvt_pk_bf16_f32 v155, v38, v39
	ds_write_b16 v148, v155 offset:11552
	v_lshrrev_b32_e32 v155, 16, v155
	ds_write_b16 v148, v155 offset:11824
	v_mul_f32_e32 v40, v40, v142
	v_mul_f32_e32 v41, v41, v142
	v_cvt_pk_bf16_f32 v156, v40, v41
	ds_write_b16 v148, v156 offset:13184
	v_lshrrev_b32_e32 v156, 16, v156
	ds_write_b16 v148, v156 offset:13456
	v_mul_f32_e32 v42, v42, v142
	v_mul_f32_e32 v43, v43, v142
	v_cvt_pk_bf16_f32 v157, v42, v43
	ds_write_b16 v148, v157 offset:13728
	v_lshrrev_b32_e32 v157, 16, v157
	ds_write_b16 v148, v157 offset:14000
	v_mul_f32_e32 v44, v44, v142
	v_mul_f32_e32 v45, v45, v142
	v_cvt_pk_bf16_f32 v158, v44, v45
	ds_write_b16 v148, v158 offset:15360
	v_lshrrev_b32_e32 v158, 16, v158
	ds_write_b16 v148, v158 offset:15632
	v_mul_f32_e32 v46, v46, v142
	v_mul_f32_e32 v47, v47, v142
	v_cvt_pk_bf16_f32 v159, v46, v47
	ds_write_b16 v148, v159 offset:15904
	v_lshrrev_b32_e32 v159, 16, v159
	ds_write_b16 v148, v159 offset:16176
	v_mul_f32_e32 v16, v16, v143
	v_mul_f32_e32 v17, v17, v143
	v_cvt_pk_bf16_f32 v152, v16, v17
	ds_write_b16 v148, v152 offset:192
	v_lshrrev_b32_e32 v152, 16, v152
	ds_write_b16 v148, v152 offset:464
	v_mul_f32_e32 v18, v18, v143
	v_mul_f32_e32 v19, v19, v143
	v_cvt_pk_bf16_f32 v153, v18, v19
	ds_write_b16 v148, v153 offset:736
	v_lshrrev_b32_e32 v153, 16, v153
	ds_write_b16 v148, v153 offset:1008
	v_mul_f32_e32 v20, v20, v143
	v_mul_f32_e32 v21, v21, v143
	v_cvt_pk_bf16_f32 v154, v20, v21
	ds_write_b16 v148, v154 offset:2368
	v_lshrrev_b32_e32 v154, 16, v154
	ds_write_b16 v148, v154 offset:2640
	v_mul_f32_e32 v22, v22, v143
	v_mul_f32_e32 v23, v23, v143
	v_cvt_pk_bf16_f32 v155, v22, v23
	ds_write_b16 v148, v155 offset:2912
	v_lshrrev_b32_e32 v155, 16, v155
	ds_write_b16 v148, v155 offset:3184
	v_mul_f32_e32 v24, v24, v143
	v_mul_f32_e32 v25, v25, v143
	v_cvt_pk_bf16_f32 v156, v24, v25
	ds_write_b16 v148, v156 offset:4544
	v_lshrrev_b32_e32 v156, 16, v156
	ds_write_b16 v148, v156 offset:4816
	v_mul_f32_e32 v26, v26, v143
	v_mul_f32_e32 v27, v27, v143
	v_cvt_pk_bf16_f32 v157, v26, v27
	ds_write_b16 v148, v157 offset:5088
	v_lshrrev_b32_e32 v157, 16, v157
	ds_write_b16 v148, v157 offset:5360
	v_mul_f32_e32 v28, v28, v143
	v_mul_f32_e32 v29, v29, v143
	v_cvt_pk_bf16_f32 v158, v28, v29
	ds_write_b16 v148, v158 offset:6720
	v_lshrrev_b32_e32 v158, 16, v158
	ds_write_b16 v148, v158 offset:6992
	v_mul_f32_e32 v30, v30, v143
	v_mul_f32_e32 v31, v31, v143
	v_cvt_pk_bf16_f32 v159, v30, v31
	ds_write_b16 v148, v159 offset:7264
	v_lshrrev_b32_e32 v159, 16, v159
	ds_write_b16 v148, v159 offset:7536
	v_mul_f32_e32 v0, v0, v143
	v_mul_f32_e32 v1, v1, v143
	v_cvt_pk_bf16_f32 v152, v0, v1
	ds_write_b16 v148, v152 offset:8896
	v_lshrrev_b32_e32 v152, 16, v152
	ds_write_b16 v148, v152 offset:9168
	v_mul_f32_e32 v2, v2, v143
	v_mul_f32_e32 v3, v3, v143
	v_cvt_pk_bf16_f32 v153, v2, v3
	ds_write_b16 v148, v153 offset:9440
	v_lshrrev_b32_e32 v153, 16, v153
	ds_write_b16 v148, v153 offset:9712
	v_mul_f32_e32 v4, v4, v143
	v_mul_f32_e32 v5, v5, v143
	v_cvt_pk_bf16_f32 v154, v4, v5
	ds_write_b16 v148, v154 offset:11072
	v_lshrrev_b32_e32 v154, 16, v154
	ds_write_b16 v148, v154 offset:11344
	v_mul_f32_e32 v6, v6, v143
	v_mul_f32_e32 v7, v7, v143
	v_cvt_pk_bf16_f32 v155, v6, v7
	ds_write_b16 v148, v155 offset:11616
	v_lshrrev_b32_e32 v155, 16, v155
	ds_write_b16 v148, v155 offset:11888
	v_mul_f32_e32 v8, v8, v143
	v_mul_f32_e32 v9, v9, v143
	v_cvt_pk_bf16_f32 v156, v8, v9
	ds_write_b16 v148, v156 offset:13248
	v_lshrrev_b32_e32 v156, 16, v156
	ds_write_b16 v148, v156 offset:13520
	v_mul_f32_e32 v10, v10, v143
	v_mul_f32_e32 v11, v11, v143
	v_cvt_pk_bf16_f32 v157, v10, v11
	ds_write_b16 v148, v157 offset:13792
	v_lshrrev_b32_e32 v157, 16, v157
	ds_write_b16 v148, v157 offset:14064
	v_mul_f32_e32 v12, v12, v143
	v_mul_f32_e32 v13, v13, v143
	v_cvt_pk_bf16_f32 v158, v12, v13
	ds_write_b16 v148, v158 offset:15424
	v_lshrrev_b32_e32 v158, 16, v158
	ds_write_b16 v148, v158 offset:15696
	v_mul_f32_e32 v14, v14, v143
	v_mul_f32_e32 v15, v15, v143
	v_cvt_pk_bf16_f32 v159, v14, v15
	ds_write_b16 v148, v159 offset:15968
	v_lshrrev_b32_e32 v159, 16, v159
	ds_write_b16 v148, v159 offset:16240
	v_and_b32_e32 v162, 31, v144
	v_lshlrev_b32_e32 v162, 1, v162
	v_sub_u32_e32 v162, v150, v162
	v_mov_b32_e32 v163, 0
	v_lshl_add_u64 v[160:161], v[138:139], 0, v[162:163]
	s_mov_b32 s100, s101
	s_mov_b32 s101, 0
	s_waitcnt lgkmcnt(0)
; DI u16 f2bf(float a) { return (u16)(pack2(a, 0.f) & 0xffffu); }
; DI int crow(int reg, int g) { return (reg & 3) + 8 * (reg >> 2) + 4 * g; }
; template <bool TR>
; DI void gemm_in_tile(const P& p, int l, int id, char* smem) {
;     ...
;     for (int cb = 0; cb < 4; ++cb) {
;       asm volatile("" ::: "memory");
;       const int tl = 128 * wc + 32 * cb + li;
;       const int tok = m0 + tl;
;       const float rs = rs_s[tl];
;       u16* dst = hy ? (p.hyT + (size_t)(n0 + 64 * wr) * HYP + tok)
;                     : (p.VT + (size_t)((tok >> 13) * 512 + (n0 - 3072) + 64 * wr) * VTP + (tok & 8191));
;       const size_t cstride = hy ? (size_t)HYP : (size_t)VTP;
; #pragma unroll
;       for (int rb = 0; rb < 2; ++rb) {
; #pragma unroll
;         for (int reg = 0; reg < 16; ++reg) {
;           const int cl = 32 * rb + crow(reg, g);
;           dst[(size_t)cl * cstride] = f2bf(acc[rb][cb][reg] * rs);
;         }
;       }
	ds_read_b128 v[0:3], v149 offset:0
	ds_read_b128 v[4:7], v149 offset:1088
	ds_read_b128 v[8:11], v149 offset:2176
	ds_read_b128 v[12:15], v149 offset:3264
	ds_read_b128 v[16:19], v149 offset:4352
	ds_read_b128 v[20:23], v149 offset:5440
	ds_read_b128 v[24:27], v149 offset:6528
	ds_read_b128 v[28:31], v149 offset:7616
	ds_read_b128 v[32:35], v149 offset:8704
	ds_read_b128 v[36:39], v149 offset:9792
	ds_read_b128 v[40:43], v149 offset:10880
	ds_read_b128 v[44:47], v149 offset:11968
	ds_read_b128 v[48:51], v149 offset:13056
	ds_read_b128 v[52:55], v149 offset:14144
	ds_read_b128 v[56:59], v149 offset:15232
	ds_read_b128 v[60:63], v149 offset:16320
	s_waitcnt lgkmcnt(15)
	global_store_dwordx4 v[160:161], v[0:3], off
	v_lshl_add_u64 v[160:161], v[160:161], 0, s[100:101]
	s_waitcnt lgkmcnt(14)
	global_store_dwordx4 v[160:161], v[4:7], off
	v_lshl_add_u64 v[160:161], v[160:161], 0, s[100:101]
	s_waitcnt lgkmcnt(13)
	global_store_dwordx4 v[160:161], v[8:11], off
	v_lshl_add_u64 v[160:161], v[160:161], 0, s[100:101]
	s_waitcnt lgkmcnt(12)
	global_store_dwordx4 v[160:161], v[12:15], off
	v_lshl_add_u64 v[160:161], v[160:161], 0, s[100:101]
	s_waitcnt lgkmcnt(11)
	global_store_dwordx4 v[160:161], v[16:19], off
	v_lshl_add_u64 v[160:161], v[160:161], 0, s[100:101]
	s_waitcnt lgkmcnt(10)
	global_store_dwordx4 v[160:161], v[20:23], off
	v_lshl_add_u64 v[160:161], v[160:161], 0, s[100:101]
	s_waitcnt lgkmcnt(9)
	global_store_dwordx4 v[160:161], v[24:27], off
	v_lshl_add_u64 v[160:161], v[160:161], 0, s[100:101]
	s_waitcnt lgkmcnt(8)
	global_store_dwordx4 v[160:161], v[28:31], off
	v_lshl_add_u64 v[160:161], v[160:161], 0, s[100:101]
	s_waitcnt lgkmcnt(7)
	global_store_dwordx4 v[160:161], v[32:35], off
	v_lshl_add_u64 v[160:161], v[160:161], 0, s[100:101]
	s_waitcnt lgkmcnt(6)
	global_store_dwordx4 v[160:161], v[36:39], off
	v_lshl_add_u64 v[160:161], v[160:161], 0, s[100:101]
	s_waitcnt lgkmcnt(5)
	global_store_dwordx4 v[160:161], v[40:43], off
	v_lshl_add_u64 v[160:161], v[160:161], 0, s[100:101]
	s_waitcnt lgkmcnt(4)
	global_store_dwordx4 v[160:161], v[44:47], off
	v_lshl_add_u64 v[160:161], v[160:161], 0, s[100:101]
	s_waitcnt lgkmcnt(3)
	global_store_dwordx4 v[160:161], v[48:51], off
	v_lshl_add_u64 v[160:161], v[160:161], 0, s[100:101]
	s_waitcnt lgkmcnt(2)
	global_store_dwordx4 v[160:161], v[52:55], off
	v_lshl_add_u64 v[160:161], v[160:161], 0, s[100:101]
	s_waitcnt lgkmcnt(1)
	global_store_dwordx4 v[160:161], v[56:59], off
	v_lshl_add_u64 v[160:161], v[160:161], 0, s[100:101]
	s_waitcnt lgkmcnt(0)
	global_store_dwordx4 v[160:161], v[60:63], off
	s_branch .LBB0_102
